# attention: one static s_setprio 1 for waves 4-7 at phase entry, per-segment P.V priority flips removed
# baseline (speedup 1.0000x reference)
; #define LAS __attribute__((address_space(3)))
; __device__ __forceinline__ void attn_phase(const Params& P, LAS unsigned char* lds, int bx, int tid_in) {
;     int tid = tid_in; asm volatile("" : "+v"(tid)); const int lane = tid & 63, wave = __builtin_amdgcn_readfirstlane(tid >> 6);
;     unsigned char* ws = P.ws;
;     bf16_t* Q = (bf16_t*)(ws + WS_Q); const bf16_t* K = (const bf16_t*)(ws + WS_K); const bf16_t* Vt = (const bf16_t*)(ws + WS_V); const bf16_t* Z = (const bf16_t*)P.out;
;     const float* tab = (const float*)(ws + WS_MISC + MISC_ATT);
;     const float lam = __builtin_bit_cast(float, __builtin_amdgcn_readfirstlane(__builtin_bit_cast(int, tab[32]))), SB = __builtin_bit_cast(float, __builtin_amdgcn_readfirstlane(__builtin_bit_cast(int, tab[33])));
;     unsigned* qctr = (unsigned*)(ws + WS_MISC + MISC_ATQ) + 64 * (bx & 7);
;     volatile LAS int* slot = (volatile LAS int*)(lds + 2 * KT_BYTES + 2 * VT_BYTES);
;     const int b = bx & 7;
;     int unext = 0; if (tid == 0) unext = (int)atomicAdd(qctr, 1u);
.LBB0_233:
	s_or_b64 exec, exec, s[6:7]
	v_mov_b32_e32 v0, v215
	v_mov_b32_e32 v1, 0x1e830000
	s_barrier
	v_readfirstlane_b32 s93, v215
	s_nop 3
	s_lshr_b32 s93, s93, 8
	s_cmp_eq_u32 s93, 0
	s_cbranch_scc1 .Lprio_done
	s_setprio 1
.Lprio_done:
	v_and_b32_e32 v137, 63, v215
	v_lshlrev_b32_e32 v137, 4, v137
	v_cmp_gt_u32_e32 vcc, 0x200, v137
	s_and_saveexec_b64 s[10:11], vcc
	global_load_dwordx4 v[138:141], v137, s[54:55]
	v_add_u32_e32 v137, 0x11100, v137
	s_waitcnt vmcnt(0)
	ds_write_b128 v137, v[138:141]
	s_waitcnt lgkmcnt(0)
	s_or_b64 exec, exec, s[10:11]
	global_load_dwordx2 v[2:3], v1, s[30:31] offset:128
	v_lshl_add_u64 v[4:5], v[208:209], 2, s[30:31]
	s_mov_b64 s[6:7], 0x1e820000
	v_mov_b32_e32 v211, 0
	v_lshl_add_u64 v[212:213], v[4:5], 0, s[6:7]
	v_readfirstlane_b32 s10, v0
	v_cmp_eq_u32_e64 s[6:7], 0, v0
	v_mov_b32_e32 v229, 0
	s_waitcnt vmcnt(0)
	v_readfirstlane_b32 s71, v2
	v_readfirstlane_b32 s72, v3
	s_and_saveexec_b64 s[8:9], s[6:7]
	s_cbranch_execz .LBB0_235
	v_mov_b32_e32 v1, 1
	global_atomic_add v229, v[212:213], v1, off sc0

; #define LAS __attribute__((address_space(3)))
; __device__ __forceinline__ unsigned cvtpk_s(float lo, float hi) { f32x2_t v = {lo, hi}; bf16x2_t b = __builtin_convertvector(v, bf16x2_t); return __builtin_bit_cast(unsigned, b); }
; template <int HF> ...
;     ...
;         float ls = 0.f;
; #pragma unroll
;         for (int r = 0; r < 16; ++r) { p[r] = __builtin_amdgcn_exp2f(p[r]); ls += p[r]; }
;         lsum[sub] += ls;
;         pw[sub][0] = (u32x4){cvtpk_s(p[0], p[1]), cvtpk_s(p[2], p[3]), cvtpk_s(p[4], p[5]), cvtpk_s(p[6], p[7])};
;         pw[sub][1] = (u32x4){cvtpk_s(p[8], p[9]), cvtpk_s(p[10], p[11]), cvtpk_s(p[12], p[13]), cvtpk_s(p[14], p[15])};
;         __builtin_amdgcn_sched_barrier(0);
;         if (sub == 0 && stage) {
;             if (HF == 0) { *(LAS u32x4*)sdst = st0; *(LAS u32x4*)(sdst + 32 * KROW) = st1; }
;             else { *(LAS u32x2*)sdst = (u32x2){st0.x, st0.y}; *(LAS u32x2*)(sdst + 8) = (u32x2){st0.z, st0.w}; *(LAS u32x2*)(sdst + 64 * VROW) = (u32x2){st1.x, st1.y}; *(LAS u32x2*)(sdst + 64 * VROW + 8) = (u32x2){st1.z, st1.w}; }
;             __builtin_amdgcn_sched_barrier(0);
;         }
;     }
;     ...
;     bf16x8 vcur = AT_VFRAG(0);
;     __builtin_amdgcn_s_setprio(1);
; #pragma unroll
;     for (int idx = 0; idx < 8; ++idx) {
;         bf16x8 vnext = vcur;
;         if (idx + 1 < 8) vnext = AT_VFRAG(idx + 1);
;         const int kk = idx >> 2, d = idx & 3;
;         o[0][d] = __builtin_amdgcn_mfma_f32_32x32x16_bf16(vcur, __builtin_bit_cast(bf16x8, pw[0][kk]), o[0][d], 0, 0, 0);
;         o[1][d] = __builtin_amdgcn_mfma_f32_32x32x16_bf16(vcur, __builtin_bit_cast(bf16x8, pw[1][kk]), o[1][d], 0, 0, 0);
;         __builtin_amdgcn_sched_barrier(0);
;         vcur = vnext;
;     }
;     __builtin_amdgcn_s_setprio(0);
.LBB0_258:
	v_exp_f32_e32 v227, v144
	v_exp_f32_e32 v248, v145
	v_exp_f32_e32 v249, v146
	v_exp_f32_e32 v250, v147
	v_add_f32_e32 v144, 0, v227
	v_exp_f32_e32 v148, v148
	v_add_f32_e32 v144, v248, v144
	v_exp_f32_e32 v149, v149
	v_add_f32_e32 v144, v249, v144
	v_exp_f32_e32 v150, v150
	v_add_f32_e32 v144, v250, v144
	v_exp_f32_e32 v151, v151
	v_add_f32_e32 v144, v148, v144
	v_exp_f32_e32 v152, v152
	v_add_f32_e32 v144, v149, v144
	v_exp_f32_e32 v153, v153
	v_add_f32_e32 v144, v150, v144
	v_exp_f32_e32 v145, v154
	v_add_f32_e32 v144, v151, v144
	v_exp_f32_e32 v154, v155
	v_add_f32_e32 v144, v152, v144
	v_exp_f32_e32 v146, v156
	v_add_f32_e32 v144, v153, v144
	v_exp_f32_e32 v155, v157
	v_add_f32_e32 v144, v145, v144
	v_exp_f32_e32 v147, v158
	v_add_f32_e32 v144, v154, v144
	v_exp_f32_e32 v156, v159
	v_add_f32_e32 v144, v146, v144
	v_exp_f32_e32 v128, v128
	v_add_f32_e32 v144, v155, v144
	v_exp_f32_e32 v129, v129
	v_add_f32_e32 v144, v147, v144
	v_exp_f32_e32 v130, v130
	v_add_f32_e32 v144, v156, v144
	v_exp_f32_e32 v131, v131
	v_add_f32_e32 v224, v224, v144
	v_cvt_pk_bf16_f32 v144, v152, v153
	v_add_f32_e32 v152, 0, v128
	v_exp_f32_e32 v132, v132
	v_add_f32_e32 v152, v129, v152
	v_exp_f32_e32 v133, v133
	v_add_f32_e32 v152, v130, v152
	v_exp_f32_e32 v134, v134
	v_add_f32_e32 v152, v131, v152
	v_exp_f32_e32 v135, v135
	v_add_f32_e32 v152, v132, v152
	v_exp_f32_e32 v136, v136
	v_add_f32_e32 v152, v133, v152
	v_exp_f32_e32 v137, v137
	v_add_f32_e32 v152, v134, v152
	v_exp_f32_e32 v138, v138
	v_add_f32_e32 v152, v135, v152
	v_exp_f32_e32 v139, v139
	v_add_f32_e32 v152, v136, v152
	v_exp_f32_e32 v140, v140
	v_add_f32_e32 v152, v137, v152
	v_exp_f32_e32 v141, v141
	v_add_f32_e32 v152, v138, v152
	v_exp_f32_e32 v142, v142
	v_add_f32_e32 v152, v139, v152
	v_exp_f32_e32 v143, v143
	v_add_f32_e32 v152, v140, v152
	v_add_f32_e32 v152, v141, v152
	v_add_f32_e32 v152, v142, v152
	v_add_f32_e32 v152, v143, v152
	v_add_f32_e32 v225, v225, v152
	v_cvt_pk_bf16_f32 v147, v147, v156
	v_cvt_pk_bf16_f32 v146, v146, v155
	v_cvt_pk_bf16_f32 v145, v145, v154
	v_cvt_pk_bf16_f32 v151, v150, v151
	v_cvt_pk_bf16_f32 v150, v148, v149
	v_cvt_pk_bf16_f32 v149, v249, v250
	v_cvt_pk_bf16_f32 v148, v227, v248
	v_cvt_pk_bf16_f32 v128, v128, v129
	v_cvt_pk_bf16_f32 v129, v130, v131
	v_cvt_pk_bf16_f32 v130, v132, v133
	v_cvt_pk_bf16_f32 v131, v134, v135
	v_cvt_pk_bf16_f32 v132, v136, v137
	v_cvt_pk_bf16_f32 v133, v138, v139
	v_cvt_pk_bf16_f32 v134, v140, v141
	v_cvt_pk_bf16_f32 v135, v142, v143
	v_add_u32_e32 v152, s91, v236
	v_add_u32_e32 v153, 0x8800, v152
	v_add_u32_e32 v154, 0x9800, v152
	v_add_u32_e32 v155, 0xa800, v152
	v_add_u32_e32 v156, 0xb800, v152
	ds_read2_b64 v[136:139], v153 offset0:0 offset1:2
	ds_read2_b64 v[140:143], v154 offset0:32 offset1:34
	ds_read2_b64 v[248:251], v155 offset0:64 offset1:66
	s_waitcnt lgkmcnt(2)
	v_mfma_f32_32x32x16_bf16 v[64:79], v[136:139], v[148:151], v[64:79]
	ds_read2_b64 v[252:255], v156 offset0:96 offset1:98
	v_mfma_f32_32x32x16_bf16 v[112:127], v[136:139], v[128:131], v[112:127]
	s_waitcnt lgkmcnt(2)
	v_mfma_f32_32x32x16_bf16 v[48:63], v[140:143], v[148:151], v[48:63]
	ds_read2_b64 v[136:139], v153 offset0:4 offset1:6
	v_mfma_f32_32x32x16_bf16 v[96:111], v[140:143], v[128:131], v[96:111]
	s_waitcnt lgkmcnt(2)
	v_mfma_f32_32x32x16_bf16 v[16:31], v[248:251], v[148:151], v[16:31]
	ds_read2_b64 v[140:143], v154 offset0:36 offset1:38
	v_mfma_f32_32x32x16_bf16 v[80:95], v[248:251], v[128:131], v[80:95]
	s_waitcnt lgkmcnt(2)
	v_mfma_f32_32x32x16_bf16 v[0:15], v[252:255], v[148:151], v[0:15]
	ds_read2_b64 v[248:251], v155 offset0:68 offset1:70
	v_mfma_f32_32x32x16_bf16 v[32:47], v[252:255], v[128:131], v[32:47]
	s_waitcnt lgkmcnt(2)
	v_mfma_f32_32x32x16_bf16 v[64:79], v[136:139], v[144:147], v[64:79]
	ds_read2_b64 v[252:255], v156 offset0:100 offset1:102
	v_mfma_f32_32x32x16_bf16 v[112:127], v[136:139], v[132:135], v[112:127]
	s_waitcnt lgkmcnt(2)
	v_mfma_f32_32x32x16_bf16 v[48:63], v[140:143], v[144:147], v[48:63]
	v_mfma_f32_32x32x16_bf16 v[96:111], v[140:143], v[132:135], v[96:111]
	s_waitcnt lgkmcnt(1)
	v_mfma_f32_32x32x16_bf16 v[16:31], v[248:251], v[144:147], v[16:31]
	v_mfma_f32_32x32x16_bf16 v[80:95], v[248:251], v[132:135], v[80:95]
	s_waitcnt lgkmcnt(0)
	v_mfma_f32_32x32x16_bf16 v[0:15], v[252:255], v[144:147], v[0:15]
	v_mfma_f32_32x32x16_bf16 v[32:47], v[252:255], v[132:135], v[32:47]

; #define LAS __attribute__((address_space(3)))
; __device__ __forceinline__ unsigned cvtpk_s(float lo, float hi) { f32x2_t v = {lo, hi}; bf16x2_t b = __builtin_convertvector(v, bf16x2_t); return __builtin_bit_cast(unsigned, b); }
; template <int HF> ...
;     ...
;         float ls = 0.f;
; #pragma unroll
;         for (int r = 0; r < 16; ++r) { p[r] = __builtin_amdgcn_exp2f(p[r]); ls += p[r]; }
;         lsum[sub] += ls;
;         pw[sub][0] = (u32x4){cvtpk_s(p[0], p[1]), cvtpk_s(p[2], p[3]), cvtpk_s(p[4], p[5]), cvtpk_s(p[6], p[7])};
;         pw[sub][1] = (u32x4){cvtpk_s(p[8], p[9]), cvtpk_s(p[10], p[11]), cvtpk_s(p[12], p[13]), cvtpk_s(p[14], p[15])};
;         __builtin_amdgcn_sched_barrier(0);
;         if (sub == 0 && stage) {
;             if (HF == 0) { *(LAS u32x4*)sdst = st0; *(LAS u32x4*)(sdst + 32 * KROW) = st1; }
;             else { *(LAS u32x2*)sdst = (u32x2){st0.x, st0.y}; *(LAS u32x2*)(sdst + 8) = (u32x2){st0.z, st0.w}; *(LAS u32x2*)(sdst + 64 * VROW) = (u32x2){st1.x, st1.y}; *(LAS u32x2*)(sdst + 64 * VROW + 8) = (u32x2){st1.z, st1.w}; }
;             __builtin_amdgcn_sched_barrier(0);
;         }
;     }
;     ...
;     bf16x8 vcur = AT_VFRAG(0);
;     __builtin_amdgcn_s_setprio(1);
; #pragma unroll
;     for (int idx = 0; idx < 8; ++idx) {
;         bf16x8 vnext = vcur;
;         if (idx + 1 < 8) vnext = AT_VFRAG(idx + 1);
;         const int kk = idx >> 2, d = idx & 3;
;         o[0][d] = __builtin_amdgcn_mfma_f32_32x32x16_bf16(vcur, __builtin_bit_cast(bf16x8, pw[0][kk]), o[0][d], 0, 0, 0);
;         o[1][d] = __builtin_amdgcn_mfma_f32_32x32x16_bf16(vcur, __builtin_bit_cast(bf16x8, pw[1][kk]), o[1][d], 0, 0, 0);
;         __builtin_amdgcn_sched_barrier(0);
;         vcur = vnext;
;     }
;     __builtin_amdgcn_s_setprio(0);
.LBB0_272:
	v_exp_f32_e32 v227, v144
	v_exp_f32_e32 v247, v145
	v_exp_f32_e32 v248, v146
	v_exp_f32_e32 v249, v147
	v_add_f32_e32 v144, 0, v227
	v_exp_f32_e32 v148, v148
	v_add_f32_e32 v144, v247, v144
	v_exp_f32_e32 v149, v149
	v_add_f32_e32 v144, v248, v144
	v_exp_f32_e32 v150, v150
	v_add_f32_e32 v144, v249, v144
	v_exp_f32_e32 v151, v151
	v_add_f32_e32 v144, v148, v144
	v_exp_f32_e32 v152, v152
	v_add_f32_e32 v144, v149, v144
	v_exp_f32_e32 v153, v153
	v_add_f32_e32 v144, v150, v144
	v_exp_f32_e32 v145, v154
	v_add_f32_e32 v144, v151, v144
	v_exp_f32_e32 v154, v155
	v_add_f32_e32 v144, v152, v144
	v_exp_f32_e32 v146, v156
	v_add_f32_e32 v144, v153, v144
	v_exp_f32_e32 v155, v157
	v_add_f32_e32 v144, v145, v144
	v_exp_f32_e32 v147, v158
	v_add_f32_e32 v144, v154, v144
	v_exp_f32_e32 v156, v159
	v_add_f32_e32 v144, v146, v144
	v_exp_f32_e32 v128, v128
	v_add_f32_e32 v144, v155, v144
	v_exp_f32_e32 v129, v129
	v_add_f32_e32 v144, v147, v144
	v_exp_f32_e32 v130, v130
	v_add_f32_e32 v144, v156, v144
	v_exp_f32_e32 v131, v131
	v_add_f32_e32 v224, v224, v144
	v_cvt_pk_bf16_f32 v144, v152, v153
	v_add_f32_e32 v152, 0, v128
	v_exp_f32_e32 v132, v132
	v_add_f32_e32 v152, v129, v152
	v_exp_f32_e32 v133, v133
	v_add_f32_e32 v152, v130, v152
	v_exp_f32_e32 v134, v134
	v_add_f32_e32 v152, v131, v152
	v_exp_f32_e32 v135, v135
	v_add_f32_e32 v152, v132, v152
	v_exp_f32_e32 v136, v136
	v_add_f32_e32 v152, v133, v152
	v_exp_f32_e32 v137, v137
	v_add_f32_e32 v152, v134, v152
	v_exp_f32_e32 v138, v138
	v_add_f32_e32 v152, v135, v152
	v_exp_f32_e32 v139, v139
	v_add_f32_e32 v152, v136, v152
	v_exp_f32_e32 v140, v140
	v_add_f32_e32 v152, v137, v152
	v_exp_f32_e32 v141, v141
	v_add_f32_e32 v152, v138, v152
	v_exp_f32_e32 v142, v142
	v_add_f32_e32 v152, v139, v152
	v_exp_f32_e32 v143, v143
	v_add_f32_e32 v152, v140, v152
	v_add_f32_e32 v152, v141, v152
	v_add_f32_e32 v152, v142, v152
	v_add_f32_e32 v152, v143, v152
	v_add_f32_e32 v225, v225, v152
	v_cvt_pk_bf16_f32 v147, v147, v156
	v_cvt_pk_bf16_f32 v146, v146, v155
	v_cvt_pk_bf16_f32 v145, v145, v154
	v_cvt_pk_bf16_f32 v151, v150, v151
	v_cvt_pk_bf16_f32 v150, v148, v149
	v_cvt_pk_bf16_f32 v149, v248, v249
	v_cvt_pk_bf16_f32 v148, v227, v247
	v_cvt_pk_bf16_f32 v128, v128, v129
	v_cvt_pk_bf16_f32 v129, v130, v131
	v_cvt_pk_bf16_f32 v130, v132, v133
	v_cvt_pk_bf16_f32 v131, v134, v135
	v_cvt_pk_bf16_f32 v132, v136, v137
	v_cvt_pk_bf16_f32 v133, v138, v139
	v_cvt_pk_bf16_f32 v134, v140, v141
	v_cvt_pk_bf16_f32 v135, v142, v143
	v_add_u32_e32 v152, s91, v236
	v_add_u32_e32 v153, 0x8800, v152
	v_add_u32_e32 v154, 0x9800, v152
	v_add_u32_e32 v155, 0xa800, v152
	v_add_u32_e32 v156, 0xb800, v152
	ds_read2_b64 v[136:139], v153 offset0:8 offset1:10
	ds_read2_b64 v[140:143], v154 offset0:40 offset1:42
	ds_read2_b64 v[248:251], v155 offset0:72 offset1:74
	s_waitcnt lgkmcnt(2)
	v_mfma_f32_32x32x16_bf16 v[64:79], v[136:139], v[148:151], v[64:79]
	ds_read2_b64 v[252:255], v156 offset0:104 offset1:106
	v_mfma_f32_32x32x16_bf16 v[112:127], v[136:139], v[128:131], v[112:127]
	s_waitcnt lgkmcnt(2)
	v_mfma_f32_32x32x16_bf16 v[48:63], v[140:143], v[148:151], v[48:63]
	ds_read2_b64 v[136:139], v153 offset0:12 offset1:14
	v_mfma_f32_32x32x16_bf16 v[96:111], v[140:143], v[128:131], v[96:111]
	s_waitcnt lgkmcnt(2)
	v_mfma_f32_32x32x16_bf16 v[16:31], v[248:251], v[148:151], v[16:31]
	ds_read2_b64 v[140:143], v154 offset0:44 offset1:46
	v_mfma_f32_32x32x16_bf16 v[80:95], v[248:251], v[128:131], v[80:95]
	s_waitcnt lgkmcnt(2)
	v_mfma_f32_32x32x16_bf16 v[0:15], v[252:255], v[148:151], v[0:15]
	ds_read2_b64 v[248:251], v155 offset0:76 offset1:78
	v_mfma_f32_32x32x16_bf16 v[32:47], v[252:255], v[128:131], v[32:47]
	s_waitcnt lgkmcnt(2)
	v_mfma_f32_32x32x16_bf16 v[64:79], v[136:139], v[144:147], v[64:79]
	ds_read2_b64 v[252:255], v156 offset0:108 offset1:110
	v_mfma_f32_32x32x16_bf16 v[112:127], v[136:139], v[132:135], v[112:127]
	s_waitcnt lgkmcnt(2)
	v_mfma_f32_32x32x16_bf16 v[48:63], v[140:143], v[144:147], v[48:63]
	v_mfma_f32_32x32x16_bf16 v[96:111], v[140:143], v[132:135], v[96:111]
	s_waitcnt lgkmcnt(1)
	v_mfma_f32_32x32x16_bf16 v[16:31], v[248:251], v[144:147], v[16:31]
	v_mfma_f32_32x32x16_bf16 v[80:95], v[248:251], v[132:135], v[80:95]
	s_waitcnt lgkmcnt(0)
	v_mfma_f32_32x32x16_bf16 v[0:15], v[252:255], v[144:147], v[0:15]
	v_mfma_f32_32x32x16_bf16 v[32:47], v[252:255], v[132:135], v[32:47]

; __device__ __forceinline__ void attn_phase(const Params& P, LAS unsigned char* lds, int bx, int tid_in) {
;     ...
; }
.LBB0_275:
	s_setprio 0
	v_lshl_add_u64 v[136:137], v[208:209], 2, s[56:57]
	s_barrier
	s_and_saveexec_b64 s[6:7], s[24:25]
	s_cbranch_execz .LBB0_283
	v_mov_b32_e32 v0, 1
	buffer_wbl2 sc1
	s_waitcnt vmcnt(0)
	buffer_inv sc1
	global_atomic_add v0, v[136:137], v0, off sc0
	s_lshl_b32 s8, s70, 1
	s_add_i32 s8, s8, -1
	s_waitcnt vmcnt(0)
	v_cmp_eq_u32_e32 vcc, s8, v0
	s_and_saveexec_b64 s[8:9], vcc
	s_cbranch_execz .LBB0_279
	s_mov_b64 s[10:11], exec
	v_mbcnt_lo_u32_b32 v0, s10, 0
	v_mbcnt_hi_u32_b32 v0, s11, v0
	v_cmp_eq_u32_e32 vcc, 0, v0
	s_and_b64 s[18:19], exec, vcc
	s_mov_b64 exec, s[18:19]
	s_cbranch_execz .LBB0_279
	s_bcnt1_i32_b64 s10, s[10:11]
	v_mov_b32_e32 v0, 0x1e828000
	v_mov_b32_e32 v1, s10
	global_atomic_add v0, v1, s[30:31] offset:2048
